# P5 sample-row tiles moved from the tail of phase 5 to the start of phase 6 on blocks with slack; dependent phase-6 tiles wait on a completion counter (release/acquire like the grid barrier)
# speedup vs baseline: 1.0106x; 1.0047x over previous
.LBB0_711:
	v_readfirstlane_b32 s6, v205
	v_readlane_b32 s2, v244, 7
	s_mul_i32 s50, s2, s6
	s_mul_hi_u32 s7, s6, s50
	s_add_i32 s6, s6, s7
	s_mul_hi_u32 s6, s49, s6
	s_mul_i32 s7, s6, s47
	s_sub_i32 s7, s49, s7
	s_add_i32 s8, s6, 1
	s_sub_i32 s9, s7, s47
	s_cmp_ge_u32 s7, s47
	s_cselect_b32 s6, s8, s6
	s_cselect_b32 s7, s9, s7
	s_add_i32 s8, s6, 1
	s_cmp_ge_u32 s7, s47
	s_cselect_b32 s6, s8, s6
	s_xor_b32 s6, s6, s48
	s_add_i32 s7, s44, 0x7f
	v_readlane_b32 s2, v244, 8
	s_sub_i32 s22, s6, s48
	s_lshr_b32 s23, s7, s2
	s_cmp_ge_i32 s22, s23
	v_readlane_b32 s2, v244, 6
	s_branch .LBB0_738
	s_mul_i32 s7, s22, s44
	s_sub_i32 s7, s2, s7
	s_add_u32 s47, s94, 0x18a88000
	s_addc_u32 s49, s95, 0
	s_add_u32 s50, s94, 0x15c88000
	s_addc_u32 s51, s95, 0
	s_mul_i32 s33, s23, s7
	s_add_u32 s52, s94, 0x13288000
	s_addc_u32 s53, s95, 0
	s_add_i32 s6, s6, s33
	s_sub_i32 s48, s6, s48
	s_mov_b64 s[6:7], 0x10000
	s_mov_b64 s[8:9], 0x10040
	s_mov_b64 s[10:11], 0x80
	s_mov_b64 s[12:13], 0x10080
	s_mov_b32 s54, 0x3ffffe0
	s_mov_b64 s[14:15], 0x15c880c0
	s_mov_b32 s17, 0
	s_mov_b64 s[18:19], 0x18a880c0
	s_mov_b64 s[20:21], 0x18a980c0
	s_mov_b64 s[24:25], 0x15c88100
	s_mov_b64 s[26:27], 0x18a88100
	s_mov_b64 s[28:29], 0x18a98100
	s_branch .LBB0_715

.LBB0_783:
	s_cmp_gt_i32 s28, 6
	s_cselect_b64 s[4:5], -1, 0
	s_cmp_lt_i32 s29, 7
	s_cselect_b64 s[6:7], -1, 0
	s_or_b64 s[4:5], s[4:5], s[6:7]
	s_and_b64 vcc, exec, s[4:5]
	s_cbranch_vccnz .LBB0_856
	s_mov_b32 s96, 0
	s_load_dword s3, s[0:1], 0x120
	s_add_u32 s4, s0, 0x120
	s_addc_u32 s5, s1, 0
	s_ashr_i32 s6, s2, 31
	v_writelane_b32 v244, s4, 4
	s_waitcnt lgkmcnt(0)
	s_and_b32 s7, s3, 7
	s_cmp_eq_u32 s7, 0
	s_cselect_b32 s44, 8, 1
	v_writelane_b32 v244, s5, 5
	s_cselect_b32 s4, 3, 0
	s_abs_i32 s47, s44
	v_cvt_f32_u32_e32 v0, s47
	v_writelane_b32 v244, s2, 6
	s_abs_i32 s49, s2
	s_sub_i32 s2, 0, s47
	v_rcp_iflag_f32_e32 v0, v0
	s_sub_i32 s8, 0, s44
	s_ashr_i32 s7, s44, 31
	s_xor_b32 s48, s6, s7
	v_mul_f32_e32 v0, 0x4f7ffffe, v0
	v_cvt_u32_f32_e32 v205, v0
	v_cvt_f32_ubyte0_e32 v0, s44
	s_abs_i32 s7, s3
	s_ashr_i32 s6, s3, 31
	v_mul_lo_u32 v1, s2, v205
	v_mul_hi_u32 v1, v205, v1
	v_add_u32_e32 v1, v205, v1
	v_mul_hi_u32 v1, s49, v1
	v_mul_lo_u32 v2, v1, s47
	v_sub_u32_e32 v2, s49, v2
	v_subrev_u32_e32 v4, s47, v2
	v_cmp_le_u32_e32 vcc, s47, v2
	v_add_u32_e32 v3, 1, v1
	v_writelane_b32 v244, s2, 7
	v_cndmask_b32_e32 v2, v2, v4, vcc
	v_rcp_iflag_f32_e32 v4, v0
	v_cndmask_b32_e32 v1, v1, v3, vcc
	v_add_u32_e32 v3, 1, v1
	v_cmp_le_u32_e32 vcc, s47, v2
	v_writelane_b32 v244, s4, 8
	s_nop 0
	v_cndmask_b32_e32 v0, v1, v3, vcc
	v_mul_f32_e32 v1, 0x4f7ffffe, v4
	v_cvt_u32_f32_e32 v1, v1
	v_xor_b32_e32 v0, s48, v0
	v_subrev_u32_e32 v206, s48, v0
	v_readfirstlane_b32 s9, v1
	s_mul_i32 s8, s8, s9
	s_mul_hi_u32 s8, s9, s8
	s_add_i32 s9, s9, s8
	s_mul_hi_u32 s8, s7, s9
	s_mul_i32 s9, s8, s44
	s_sub_i32 s7, s7, s9
	s_add_i32 s9, s8, 1
	s_sub_i32 s10, s7, s44
	s_cmp_ge_u32 s7, s44
	s_cselect_b32 s8, s9, s8
	s_cselect_b32 s7, s10, s7
	s_add_i32 s9, s8, 1
	s_cmp_ge_u32 s7, s44
	s_cselect_b32 s7, s9, s8
	s_add_i32 s8, s44, 0x1ff
	s_lshr_b32 s51, s8, s4
	s_xor_b32 s7, s7, s6
	v_cmp_le_i32_e32 vcc, s51, v206
	s_sub_i32 s46, s7, s6
	s_branch .LBB0_711_m6
	s_add_u32 s52, s94, 0x18a88000
	v_mul_lo_u32 v1, v206, s44
	v_readlane_b32 s2, v244, 6
	s_addc_u32 s53, s95, 0
	s_add_u32 s6, s94, 0x15c88000
	v_sub_u32_e32 v1, s2, v1
	v_mul_lo_u32 v207, s51, v1
	s_addc_u32 s7, s95, 0
	s_add_u32 s8, s94, 0x13288000
	v_add_u32_e32 v0, v0, v207
	s_addc_u32 s9, s95, 0
	v_subrev_u32_e32 v208, s48, v0
	s_mov_b64 s[10:11], 0x10000
	s_mov_b64 s[12:13], 0x10040
	s_waitcnt vmcnt(4)
	v_mov_b32_e32 v129, 0
	s_mov_b32 s50, 0x80000
	s_mov_b32 s2, 0x82000
	s_mov_b32 s36, 0x84000
	s_mov_b32 s37, 0x86000
	s_mov_b32 s38, 0x90000
	s_mov_b32 s39, 0x92000
	s_mov_b32 s96, 0x94000
	s_mov_b32 s97, 0x96000
	s_mov_b32 s3, 0xa0000
	s_mov_b32 s4, 0xa2000
	s_mov_b32 s5, 0xa4000
	s_mov_b32 s45, 0xa6000
	s_mov_b32 s54, 0xb0000
	s_mov_b32 s55, 0xb2000
	s_mov_b32 s76, 0xc4000
	s_mov_b32 s77, 0xc6000
	s_mov_b32 s78, 0xd0000
	s_mov_b32 s79, 0xd2000
	s_mov_b32 s80, 0xd4000
	s_mov_b32 s81, 0xd6000
	s_mov_b32 s82, 0xe0000
	s_mov_b32 s83, 0xe2000
	s_mov_b32 s84, 0xe4000
	s_mov_b32 s85, 0xe6000
	s_mov_b32 s86, 0xf0000
	s_mov_b32 s87, 0xf2000
	s_mov_b32 s88, 0xf4000
	s_mov_b32 s89, 0xf6000
	s_mov_b64 s[14:15], 0x15cb8080
	s_mov_b64 s[16:17], 0x18a88080
	s_mov_b64 s[18:19], 0x18a98080
	s_mov_b64 s[20:21], 0x15c880c0
	s_mov_b64 s[24:25], 0x15c980c0
	s_mov_b64 s[26:27], 0x15ca80c0
	s_mov_b64 s[28:29], 0x15cb80c0
	s_mov_b64 s[30:31], 0x18a880c0
	s_mov_b64 s[34:35], 0x18a980c0
	s_branch .LBB0_707_m6

.LBB0_711_m6:
	v_readfirstlane_b32 s6, v205
	v_readlane_b32 s2, v244, 7
	s_mul_i32 s50, s2, s6
	s_mul_hi_u32 s7, s6, s50
	s_add_i32 s6, s6, s7
	s_mul_hi_u32 s6, s49, s6
	s_mul_i32 s7, s6, s47
	s_sub_i32 s7, s49, s7
	s_add_i32 s8, s6, 1
	s_sub_i32 s9, s7, s47
	s_cmp_ge_u32 s7, s47
	s_cselect_b32 s6, s8, s6
	s_cselect_b32 s7, s9, s7
	s_add_i32 s8, s6, 1
	s_cmp_ge_u32 s7, s47
	s_cselect_b32 s6, s8, s6
	s_xor_b32 s6, s6, s48
	s_add_i32 s7, s44, 0x7f
	v_readlane_b32 s2, v244, 8
	s_sub_i32 s22, s6, s48
	s_sub_i32 s22, s22, 16
	s_lshr_b32 s23, s7, s2
	s_cmp_ge_i32 s22, s23
	v_readlane_b32 s2, v244, 6
	s_cbranch_scc1 .Lp6s_end
	s_cmp_lt_i32 s22, 0
	s_cbranch_scc1 .Lp6s_end
	s_mul_i32 s7, s22, s44
	s_sub_i32 s7, s2, s7
	s_sub_i32 s7, s7, 0x80
	s_mov_b32 s96, 1
	s_add_u32 s47, s94, 0x18a88000
	s_addc_u32 s49, s95, 0
	s_add_u32 s50, s94, 0x15c88000
	s_addc_u32 s51, s95, 0
	s_mul_i32 s33, s23, s7
	s_add_u32 s52, s94, 0x13288000
	s_addc_u32 s53, s95, 0
	s_add_i32 s6, s6, s33
	s_sub_i32 s48, s6, s48
	s_sub_i32 s48, s48, 16
	s_mov_b64 s[6:7], 0x10000
	s_mov_b64 s[8:9], 0x10040
	s_mov_b64 s[10:11], 0x80
	s_mov_b64 s[12:13], 0x10080
	s_mov_b32 s54, 0x3ffffe0
	s_mov_b64 s[14:15], 0x15c880c0
	s_mov_b32 s17, 0
	s_mov_b64 s[18:19], 0x18a880c0
	s_mov_b64 s[20:21], 0x18a980c0
	s_mov_b64 s[24:25], 0x15c88100
	s_mov_b64 s[26:27], 0x18a88100
	s_mov_b64 s[28:29], 0x18a98100
	s_branch .LBB0_715_m6

.Lp6s_end:
	s_cmp_eq_u32 s96, 1
	s_cbranch_scc0 .Lp6s_nosig
	s_waitcnt vmcnt(0) lgkmcnt(0)
	buffer_wbl2 sc1
	s_waitcnt vmcnt(0)
	s_barrier
	s_and_saveexec_b64 s[6:7], s[56:57]
	v_mov_b32_e32 v0, 0x7000
	v_mov_b32_e32 v1, 1
	global_atomic_add v0, v1, s[94:95]
	s_waitcnt vmcnt(0)
	s_or_b64 exec, exec, s[6:7]
.Lp6s_nosig:
	s_load_dword s3, s[0:1], 0x120
	s_add_u32 s4, s0, 0x120
	s_addc_u32 s5, s1, 0
	s_movk_i32 s47, 0x43f
	s_waitcnt lgkmcnt(0)
	s_and_b32 s6, s3, 7
	s_cmp_eq_u32 s6, 0
	s_cselect_b32 s10, 8, 1
	s_cselect_b32 s6, 3, 0
	s_abs_i32 s7, s10
	v_cvt_f32_u32_e32 v0, s7
	v_cvt_f32_ubyte0_e32 v1, s10
	v_rcp_iflag_f32_e32 v1, v1
	s_xor_b32 s9, s2, s10
	v_rcp_iflag_f32_e32 v0, v0
	s_ashr_i32 s11, s9, 31
	v_mul_f32_e32 v1, 0x4f7ffffe, v1
	v_cvt_u32_f32_e32 v1, v1
	v_mul_f32_e32 v0, 0x4f7ffffe, v0
	v_cvt_u32_f32_e32 v0, v0
	s_sub_i32 s9, 0, s7
	s_abs_i32 s8, s2
	v_readfirstlane_b32 s12, v1
	v_mul_lo_u32 v2, s9, v0
	v_mul_hi_u32 v2, v0, v2
	v_add_u32_e32 v0, v0, v2
	s_sub_i32 s9, 0, s10
	v_mul_hi_u32 v0, s8, v0
	s_mul_i32 s9, s9, s12
	v_mul_lo_u32 v2, v0, s7
	s_mul_hi_u32 s9, s12, s9
	v_sub_u32_e32 v2, s8, v2
	s_abs_i32 s8, s3
	s_add_i32 s12, s12, s9
	s_mul_hi_u32 s9, s8, s12
	v_subrev_u32_e32 v4, s7, v2
	v_cmp_le_u32_e32 vcc, s7, v2
	s_mul_i32 s12, s9, s10
	v_add_u32_e32 v3, 1, v0
	v_cndmask_b32_e32 v2, v2, v4, vcc
	s_sub_i32 s8, s8, s12
	v_cndmask_b32_e32 v0, v0, v3, vcc
	v_cmp_le_u32_e32 vcc, s7, v2
	s_ashr_i32 s7, s3, 31
	s_add_i32 s12, s9, 1
	s_sub_i32 s13, s8, s10
	s_cmp_ge_u32 s8, s10
	s_cselect_b32 s9, s12, s9
	s_cselect_b32 s8, s13, s8
	s_add_i32 s12, s9, 1
	s_cmp_ge_u32 s8, s10
	v_add_u32_e32 v3, 1, v0
	s_cselect_b32 s8, s12, s9
	v_cndmask_b32_e32 v0, v0, v3, vcc
	s_xor_b32 s8, s8, s7
	v_xor_b32_e32 v0, s11, v0
	s_sub_i32 s33, s8, s7
	s_add_i32 s7, s10, 0x43f
	v_subrev_u32_e32 v76, s11, v0
	s_lshr_b32 s46, s7, s6
	v_cmp_le_i32_e32 vcc, s46, v76
	s_cbranch_vccnz .LBB0_811
	s_add_u32 s6, s94, 0x13288000
	s_addc_u32 s7, s95, 0
	s_add_u32 s48, s94, 0x19288000
	s_addc_u32 s49, s95, 0
	v_mul_lo_u32 v1, v76, s10
	s_add_u32 s50, s94, 0x19e88000
	v_sub_u32_e32 v1, s2, v1
	s_addc_u32 s51, s95, 0
	v_mul_lo_u32 v77, s46, v1
	s_add_u32 s8, s94, 0x8008000
	v_add_u32_e32 v0, v0, v77
	s_addc_u32 s9, s95, 0
	v_subrev_u32_e32 v78, s11, v0
	s_mov_b64 s[10:11], 0x10000
	s_mov_b64 s[12:13], 0x10040
	s_mov_b64 s[14:15], 0x80
	s_mov_b64 s[16:17], 0x10080
	s_mov_b32 s52, 0x3ffffc0
	s_mov_b64 s[18:19], 0x132880c0
	s_mov_b64 s[20:21], 0x132980c0
	s_mov_b64 s[22:23], 0x192880c0
	s_mov_b64 s[24:25], 0x192980c0
	s_mov_b64 s[26:27], 0x13288100
	s_mov_b64 s[28:29], 0x13298100
	s_mov_b64 s[30:31], 0x19288100
	s_mov_b64 s[34:35], 0x19298100
	v_mov_b32_e32 v65, 0
	s_mov_b64 s[36:37], 0xc0
	s_branch .LBB0_787

.LBB0_787:
	v_add_u32_e32 v0, v76, v77
	v_cmp_lt_i32_e32 vcc, s47, v0
	s_cbranch_vccnz .LBB0_786
	v_readfirstlane_b32 s38, v0
	s_cmpk_gt_i32 s38, 0x3ff
	s_cbranch_scc0 .Lp6w_go
	v_mov_b32_e32 v1, 0x7000
	s_mov_b32 s39, 0
.Lp6w_spin:
	global_load_dword v2, v1, s[94:95] sc1
	s_waitcnt vmcnt(0)
	v_readfirstlane_b32 s40, v2
	s_cmp_ge_u32 s40, 0x80
	s_cbranch_scc1 .Lp6w_done
	s_sleep 4
	s_add_u32 s39, s39, 1
	s_cmp_lt_u32 s39, 0x8000
	s_cbranch_scc1 .Lp6w_spin
.Lp6w_done:
	buffer_inv sc1
	s_waitcnt vmcnt(0)
.Lp6w_go:
	s_ashr_i32 s39, s38, 31
	s_lshr_b32 s39, s39, 25
	s_add_i32 s39, s38, s39
	s_ashr_i32 s44, s39, 7
	s_lshl_b32 s40, s44, 3
	s_and_b32 s39, s39, 0xffffff80
	s_sub_i32 s41, 0x44, s40
	s_cmpk_gt_i32 s38, 0x3ff
	s_cselect_b32 s41, s41, 8
	s_abs_i32 s38, s41
	v_cvt_f32_u32_e32 v1, s38
	v_subrev_u32_e32 v0, s39, v0
	s_sub_i32 s39, 0, s38
	v_sub_u32_e32 v2, 0, v0
	v_rcp_iflag_f32_e32 v1, v1
	v_max_i32_e32 v2, v0, v2
	v_xor_b32_e32 v3, s41, v0
	v_ashrrev_i32_e32 v3, 31, v3
	v_mul_f32_e32 v1, 0x4f7ffffe, v1
	v_cvt_u32_f32_e32 v1, v1
	v_mov_b32_e32 v8, v204
	v_add_u32_e32 v0, s40, v0
	v_mul_lo_u32 v4, s39, v1
	v_mul_hi_u32 v4, v1, v4
	v_add_u32_e32 v1, v1, v4
	v_mul_hi_u32 v1, v2, v1
	v_mul_lo_u32 v4, v1, s38
	v_sub_u32_e32 v2, v2, v4
	v_add_u32_e32 v4, 1, v1
	v_subrev_u32_e32 v5, s38, v2
	v_cmp_le_u32_e32 vcc, s38, v2
	s_mulk_i32 s44, 0x78
	v_and_b32_e32 v9, 31, v8
	v_cndmask_b32_e32 v1, v1, v4, vcc
	v_cndmask_b32_e32 v2, v2, v5, vcc
	v_add_u32_e32 v4, 1, v1
	v_cmp_le_u32_e32 vcc, s38, v2
	v_bfe_u32 v2, v8, 4, 2
	v_bitop3_b32 v2, v2, v8, 3 bitop3:0x78
	v_cndmask_b32_e32 v1, v1, v4, vcc
	v_xor_b32_e32 v1, v1, v3
	v_sub_u32_e32 v1, v1, v3
	v_ashrrev_i32_e32 v3, 6, v8
	v_readfirstlane_b32 s38, v1
	v_lshlrev_b32_e32 v5, 9, v8
	s_mul_i32 s45, s41, s38
	s_ashr_i32 s39, s38, 31
	v_lshlrev_b32_e32 v2, 3, v2
	v_lshlrev_b32_e32 v4, 16, v3
	v_and_b32_e32 v5, 0x7800, v5
	v_subrev_u32_e32 v0, s45, v0
	s_lshl_b64 s[40:41], s[38:39], 19
	v_or3_b32 v2, v5, v4, v2
	v_ashrrev_i32_e32 v1, 31, v0
	s_add_u32 s42, s48, s40
	v_lshl_add_u32 v64, v3, 11, 32
	v_ashrrev_i32_e32 v3, 31, v2
	v_lshlrev_b64 v[66:67], 18, v[0:1]
	v_lshlrev_b64 v[0:1], 19, v[0:1]
	s_addc_u32 s43, s49, s41
	v_lshlrev_b64 v[2:3], 1, v[2:3]
	v_lshl_add_u64 v[0:1], s[6:7], 0, v[0:1]
	v_lshl_add_u64 v[4:5], s[42:43], 0, v[2:3]
	v_readfirstlane_b32 s42, v64
	v_add_u32_e32 v11, 0x400, v64
	v_add_u32_e32 v10, 0x2000, v64
	v_lshl_add_u64 v[0:1], v[0:1], 0, v[2:3]
	s_mov_b32 m0, s42
	v_readfirstlane_b32 s42, v11
	v_lshl_add_u64 v[6:7], v[0:1], 0, s[10:11]
	s_mov_b32 m0, s42
	v_readfirstlane_b32 s42, v10
	v_add_u32_e32 v10, 0x2400, v64
	s_mov_b32 m0, s42
	v_readfirstlane_b32 s42, v10
	v_add_u32_e32 v10, 0x4000, v64
	v_lshl_add_u64 v[6:7], v[4:5], 0, s[10:11]
	s_mov_b32 m0, s42
	v_readfirstlane_b32 s42, v10
	v_add_u32_e32 v10, 0x4400, v64
	v_lshl_add_u64 v[6:7], v[0:1], 0, 64
	s_mov_b32 m0, s42
	v_readfirstlane_b32 s42, v10
	v_add_u32_e32 v10, 0x6000, v64
	v_lshl_add_u64 v[6:7], v[0:1], 0, s[12:13]
	s_mov_b32 m0, s42
	v_readfirstlane_b32 s42, v10
	v_add_u32_e32 v10, 0x6400, v64
	v_lshl_add_u64 v[6:7], v[4:5], 0, 64
	s_mov_b32 m0, s42
	v_readfirstlane_b32 s42, v10
	v_add_u32_e32 v10, 0x8000, v64
	v_lshl_add_u64 v[6:7], v[4:5], 0, s[12:13]
	s_mov_b32 m0, s42
	v_readfirstlane_b32 s42, v10
	v_lshl_add_u64 v[6:7], v[0:1], 0, s[14:15]
	s_mov_b32 m0, s42
	v_lshl_add_u64 v[0:1], v[0:1], 0, s[16:17]
	v_add_u32_e32 v6, 0x8400, v64
	s_add_u32 s40, s94, s40
	v_readfirstlane_b32 s42, v6
	v_add_u32_e32 v6, 0xa000, v64
	s_mov_b32 m0, s42
	v_readfirstlane_b32 s42, v6
	v_lshl_add_u64 v[0:1], v[4:5], 0, s[14:15]
	s_mov_b32 m0, s42
	s_addc_u32 s41, s95, s41
	v_lshl_add_u64 v[0:1], v[4:5], 0, s[16:17]
	v_add_u32_e32 v4, 0xa400, v64
	v_lshrrev_b32_e32 v5, 1, v8
	v_readfirstlane_b32 s42, v4
	s_mov_b32 m0, s42
	v_bfe_u32 v4, v8, 2, 2
	v_bfe_u32 v0, v8, 5, 1
	v_lshrrev_b32_e32 v1, 2, v8
	v_bitop3_b32 v1, v0, v1, 3 bitop3:0x78
	v_bitop3_b32 v0, v0, v4, 2 bitop3:0x36
	v_lshlrev_b32_e32 v82, 4, v0
	v_subrev_u32_e32 v0, s45, v78
	v_subrev_u32_e32 v0, s44, v0
	v_lshlrev_b32_e32 v81, 4, v1
	v_ashrrev_i32_e32 v1, 31, v0
	v_lshlrev_b64 v[0:1], 19, v[0:1]
	v_and_or_b32 v5, v5, s52, v9
	v_lshl_add_u64 v[0:1], s[94:95], 0, v[0:1]
	v_lshlrev_b32_e32 v79, 6, v5
	v_lshlrev_b32_e32 v5, 6, v8
	v_lshl_add_u64 v[70:71], v[0:1], 0, v[2:3]
	v_mov_b32_e32 v0, 0
	s_mov_b32 s54, 0
	s_mov_b32 s53, 1
	v_and_b32_e32 v80, 0x17c0, v5
	v_lshl_add_u64 v[68:69], s[40:41], 0, v[2:3]
	s_mov_b64 s[40:41], 0
	v_mov_b32_e32 v1, v0
	v_mov_b32_e32 v2, v0
	v_mov_b32_e32 v3, v0
	v_mov_b32_e32 v4, v0
	v_mov_b32_e32 v5, v0
	v_mov_b32_e32 v6, v0
	v_mov_b32_e32 v7, v0
	v_mov_b32_e32 v8, v0
	v_mov_b32_e32 v9, v0
	v_mov_b32_e32 v10, v0
	v_mov_b32_e32 v11, v0
	v_mov_b32_e32 v12, v0
	v_mov_b32_e32 v13, v0
	v_mov_b32_e32 v14, v0
	v_mov_b32_e32 v15, v0
	v_mov_b32_e32 v16, v0
	v_mov_b32_e32 v17, v0
	v_mov_b32_e32 v18, v0
	v_mov_b32_e32 v19, v0
	v_mov_b32_e32 v20, v0
	v_mov_b32_e32 v21, v0
	v_mov_b32_e32 v22, v0
	v_mov_b32_e32 v23, v0
	v_mov_b32_e32 v24, v0
	v_mov_b32_e32 v25, v0
	v_mov_b32_e32 v26, v0
	v_mov_b32_e32 v27, v0
	v_mov_b32_e32 v28, v0
	v_mov_b32_e32 v29, v0
	v_mov_b32_e32 v30, v0
	v_mov_b32_e32 v31, v0
	v_mov_b32_e32 v32, v0
	v_mov_b32_e32 v33, v0
	v_mov_b32_e32 v34, v0
	v_mov_b32_e32 v35, v0
	v_mov_b32_e32 v36, v0
	v_mov_b32_e32 v37, v0
	v_mov_b32_e32 v38, v0
	v_mov_b32_e32 v39, v0
	v_mov_b32_e32 v40, v0
	v_mov_b32_e32 v41, v0
	v_mov_b32_e32 v42, v0
	v_mov_b32_e32 v43, v0
	v_mov_b32_e32 v44, v0
	v_mov_b32_e32 v45, v0
	v_mov_b32_e32 v46, v0
	v_mov_b32_e32 v47, v0
	v_mov_b32_e32 v48, v0
	v_mov_b32_e32 v49, v0
	v_mov_b32_e32 v50, v0
	v_mov_b32_e32 v51, v0
	v_mov_b32_e32 v52, v0
	v_mov_b32_e32 v53, v0
	v_mov_b32_e32 v54, v0
	v_mov_b32_e32 v55, v0
	v_mov_b32_e32 v56, v0
	v_mov_b32_e32 v57, v0
	v_mov_b32_e32 v58, v0
	v_mov_b32_e32 v59, v0
	v_mov_b32_e32 v60, v0
	v_mov_b32_e32 v61, v0
	v_mov_b32_e32 v62, v0
	v_mov_b32_e32 v63, v0
	v_add3_u32 v140, v79, v81, 32
	v_add3_u32 v141, v79, v82, 32
	v_add_u32_e32 v142, 0x2020, v80
	v_add_u32_e32 v143, v142, v82
	v_add_u32_e32 v142, v142, v81
	v_subrev_u32_e32 v144, s94, v70
	v_subrev_u32_e32 v146, s94, v68
	v_add_u32_e32 v144, 0x13288000, v144
	v_add_u32_e32 v146, 0x19288000, v146
	v_add_u32_e32 v145, 0x10000, v144
	v_add_u32_e32 v147, 0x10000, v146
	v_readfirstlane_b32 s64, v64
	s_nop 0
	s_add_u32 s65, s64, 0x2000
	s_mov_b64 s[60:61], s[94:95]
	s_add_u32 s62, s94, 64
	s_addc_u32 s63, s95, 0
	v_bfe_u32 v148, v204, 2, 4
	v_lshlrev_b32_e32 v148, 7, v148
	s_mov_b32 s70, 0
	s_movk_i32 s71, 0x800
	v_xad_u32 v149, s70, v148, v146
	v_xad_u32 v150, s71, v148, v147
	s_add_u32 m0, s64, 0x0
	s_nop 0
	global_load_lds_dwordx4 v144, s[60:61]
	s_add_u32 m0, s64, 0x4000
	s_nop 0
	global_load_lds_dwordx4 v144, s[62:63]
	s_add_u32 m0, s64, 0x400
	s_nop 0
	global_load_lds_dwordx4 v145, s[60:61]
	s_add_u32 m0, s64, 0x4400
	s_nop 0
	global_load_lds_dwordx4 v145, s[62:63]
	s_add_u32 m0, s65, 0x0
	s_nop 0
	global_load_lds_dwordx4 v149, s[94:95]
	s_add_u32 m0, s65, 0x3fc0
	s_nop 0
	global_load_lds_dwordx4 v149, s[94:95] offset:64
	s_add_u32 m0, s65, 0x400
	s_nop 0
	global_load_lds_dwordx4 v150, s[94:95]
	s_add_u32 m0, s65, 0x43c0
	s_nop 0
	global_load_lds_dwordx4 v150, s[94:95] offset:64
	s_add_u32 s70, s70, 0x80
	s_xor_b32 s71, s70, 0x800
	s_add_u32 s60, s60, 128
	s_addc_u32 s61, s61, 0
	s_add_u32 s62, s62, 128
	s_addc_u32 s63, s63, 0
	v_xad_u32 v149, s70, v148, v146
	v_xad_u32 v150, s71, v148, v147
	s_add_u32 m0, s64, 0x8000
	s_nop 0
	global_load_lds_dwordx4 v144, s[60:61]
	s_add_u32 m0, s64, 0xc000
	s_nop 0
	global_load_lds_dwordx4 v144, s[62:63]
	s_add_u32 m0, s64, 0x8400
	s_nop 0
	global_load_lds_dwordx4 v145, s[60:61]
	s_add_u32 m0, s64, 0xc400
	s_nop 0
	global_load_lds_dwordx4 v145, s[62:63]
	s_add_u32 m0, s65, 0x8000
	s_nop 0
	global_load_lds_dwordx4 v149, s[94:95]
	s_add_u32 m0, s65, 0xbfc0
	s_nop 0
	global_load_lds_dwordx4 v149, s[94:95] offset:64
	s_add_u32 m0, s65, 0x8400
	s_nop 0
	global_load_lds_dwordx4 v150, s[94:95]
	s_add_u32 m0, s65, 0xc3c0
	s_nop 0
	global_load_lds_dwordx4 v150, s[94:95] offset:64
	s_add_u32 s70, s70, 0x80
	s_xor_b32 s71, s70, 0x800
	s_add_u32 s60, s60, 128
	s_addc_u32 s61, s61, 0
	s_add_u32 s62, s62, 128
	s_addc_u32 s63, s63, 0
	s_waitcnt vmcnt(9)
	s_barrier
	ds_read_b128 v[108:111], v142 offset:0
	ds_read_b128 v[112:115], v142 offset:2048
	ds_read_b128 v[116:119], v140 offset:0
	ds_read_b128 v[120:123], v140 offset:2048
	s_waitcnt lgkmcnt(0)
	s_setprio 1
	v_mfma_f32_32x32x16_bf16 v[48:63], v[116:119], v[108:111], v[48:63]
	v_mfma_f32_32x32x16_bf16 v[32:47], v[116:119], v[112:115], v[32:47]
	v_mfma_f32_32x32x16_bf16 v[16:31], v[120:123], v[108:111], v[16:31]
	v_mfma_f32_32x32x16_bf16 v[0:15], v[120:123], v[112:115], v[0:15]
	s_setprio 0
	ds_read_b128 v[124:127], v143 offset:0
	ds_read_b128 v[128:131], v143 offset:2048
	ds_read_b128 v[132:135], v141 offset:0
	ds_read_b128 v[136:139], v141 offset:2048
	s_waitcnt vmcnt(8) lgkmcnt(0)
	s_barrier
	ds_read_b128 v[108:111], v142 offset:16384
	ds_read_b128 v[112:115], v142 offset:18432
	ds_read_b128 v[116:119], v140 offset:16384
	ds_read_b128 v[120:123], v140 offset:18432
	s_setprio 1
	v_mfma_f32_32x32x16_bf16 v[48:63], v[132:135], v[124:127], v[48:63]
	v_mfma_f32_32x32x16_bf16 v[32:47], v[132:135], v[128:131], v[32:47]
	v_mfma_f32_32x32x16_bf16 v[16:31], v[136:139], v[124:127], v[16:31]
	v_mfma_f32_32x32x16_bf16 v[0:15], v[136:139], v[128:131], v[0:15]
	s_setprio 0
	s_waitcnt lgkmcnt(0)
	s_setprio 1
	v_mfma_f32_32x32x16_bf16 v[48:63], v[116:119], v[108:111], v[48:63]
	v_mfma_f32_32x32x16_bf16 v[32:47], v[116:119], v[112:115], v[32:47]
	v_mfma_f32_32x32x16_bf16 v[16:31], v[120:123], v[108:111], v[16:31]
	v_mfma_f32_32x32x16_bf16 v[0:15], v[120:123], v[112:115], v[0:15]
	s_setprio 0
	ds_read_b128 v[124:127], v143 offset:16384
	ds_read_b128 v[128:131], v143 offset:18432
	ds_read_b128 v[132:135], v141 offset:16384
	ds_read_b128 v[136:139], v141 offset:18432
	s_waitcnt vmcnt(1) lgkmcnt(0)
	s_barrier
	ds_read_b128 v[108:111], v142 offset:32768
	ds_read_b128 v[112:115], v142 offset:34816
	ds_read_b128 v[116:119], v140 offset:32768
	ds_read_b128 v[120:123], v140 offset:34816
	s_setprio 1
	v_mfma_f32_32x32x16_bf16 v[48:63], v[132:135], v[124:127], v[48:63]
	v_mfma_f32_32x32x16_bf16 v[32:47], v[132:135], v[128:131], v[32:47]
	v_mfma_f32_32x32x16_bf16 v[16:31], v[136:139], v[124:127], v[16:31]
	v_mfma_f32_32x32x16_bf16 v[0:15], v[136:139], v[128:131], v[0:15]
	s_setprio 0
	s_add_u32 m0, s64, 0x0
	s_nop 0
	global_load_lds_dwordx4 v144, s[60:61]
	s_add_u32 m0, s64, 0x4000
	s_nop 0
	global_load_lds_dwordx4 v144, s[62:63]
	s_add_u32 m0, s64, 0x400
	s_nop 0
	global_load_lds_dwordx4 v145, s[60:61]
	s_add_u32 m0, s64, 0x4400
	s_nop 0
	global_load_lds_dwordx4 v145, s[62:63]
	s_waitcnt lgkmcnt(0)
	s_setprio 1
	v_mfma_f32_32x32x16_bf16 v[48:63], v[116:119], v[108:111], v[48:63]
	v_mfma_f32_32x32x16_bf16 v[32:47], v[116:119], v[112:115], v[32:47]
	v_mfma_f32_32x32x16_bf16 v[16:31], v[120:123], v[108:111], v[16:31]
	v_mfma_f32_32x32x16_bf16 v[0:15], v[120:123], v[112:115], v[0:15]
	s_setprio 0
	ds_read_b128 v[124:127], v143 offset:32768
	ds_read_b128 v[128:131], v143 offset:34816
	ds_read_b128 v[132:135], v141 offset:32768
	ds_read_b128 v[136:139], v141 offset:34816
	v_xad_u32 v149, s70, v148, v146
	v_xad_u32 v150, s71, v148, v147
	s_add_u32 m0, s65, 0x0
	s_nop 0
	global_load_lds_dwordx4 v149, s[94:95]
	s_add_u32 m0, s65, 0x3fc0
	s_nop 0
	global_load_lds_dwordx4 v149, s[94:95] offset:64
	s_add_u32 m0, s65, 0x400
	s_nop 0
	global_load_lds_dwordx4 v150, s[94:95]
	s_add_u32 m0, s65, 0x43c0
	s_nop 0
	global_load_lds_dwordx4 v150, s[94:95] offset:64
	s_add_u32 s70, s70, 0x80
	s_xor_b32 s71, s70, 0x800
	s_add_u32 s60, s60, 128
	s_addc_u32 s61, s61, 0
	s_add_u32 s62, s62, 128
	s_addc_u32 s63, s63, 0
	s_waitcnt vmcnt(8) lgkmcnt(0)
	s_barrier
	ds_read_b128 v[108:111], v142 offset:49152
	ds_read_b128 v[112:115], v142 offset:51200
	ds_read_b128 v[116:119], v140 offset:49152
	ds_read_b128 v[120:123], v140 offset:51200
	s_setprio 1
	v_mfma_f32_32x32x16_bf16 v[48:63], v[132:135], v[124:127], v[48:63]
	v_mfma_f32_32x32x16_bf16 v[32:47], v[132:135], v[128:131], v[32:47]
	v_mfma_f32_32x32x16_bf16 v[16:31], v[136:139], v[124:127], v[16:31]
	v_mfma_f32_32x32x16_bf16 v[0:15], v[136:139], v[128:131], v[0:15]
	s_setprio 0
	s_waitcnt lgkmcnt(0)
	s_setprio 1
	v_mfma_f32_32x32x16_bf16 v[48:63], v[116:119], v[108:111], v[48:63]
	v_mfma_f32_32x32x16_bf16 v[32:47], v[116:119], v[112:115], v[32:47]
	v_mfma_f32_32x32x16_bf16 v[16:31], v[120:123], v[108:111], v[16:31]
	v_mfma_f32_32x32x16_bf16 v[0:15], v[120:123], v[112:115], v[0:15]
	s_setprio 0
	ds_read_b128 v[124:127], v143 offset:49152
	ds_read_b128 v[128:131], v143 offset:51200
	ds_read_b128 v[132:135], v141 offset:49152
	ds_read_b128 v[136:139], v141 offset:51200
	s_mov_b32 s69, 14
